# P3 step 6: T = A.V' MFMA chain software-pipelined over three operand register slots
# baseline (speedup 1.0000x reference)
.LBB0_606:
	s_waitcnt lgkmcnt(0)
	s_barrier
	s_and_b64 vcc, exec, s[76:77]
	s_cbranch_vccnz .Lmy_t8
	s_and_b64 vcc, exec, s[78:79]
	s_cbranch_vccnz .Lmy_t6
	s_and_b64 vcc, exec, s[72:73]
	s_cbranch_vccnz .Lmy_t4
	ds_read_b128 v[4:7], v249
	ds_read_b64_tr_b16 v[8:9], v250
	ds_read_b64_tr_b16 v[10:11], v250 offset:576
	ds_read_b128 v[82:85], v249 offset:32
	ds_read_b64_tr_b16 v[86:87], v250 offset:2304
	ds_read_b64_tr_b16 v[88:89], v250 offset:2880
	s_waitcnt lgkmcnt(3)
	v_mfma_f32_32x32x16_bf16 v[66:81], v[4:7], v[8:11], 0
	s_waitcnt lgkmcnt(0)
	v_mfma_f32_32x32x16_bf16 v[66:81], v[82:85], v[86:89], v[66:81]
	s_branch .LBB0_610
.Lmy_t4:
	ds_read_b128 v[4:7], v249
	ds_read_b64_tr_b16 v[8:9], v250
	ds_read_b64_tr_b16 v[10:11], v250 offset:576
	ds_read_b128 v[82:85], v249 offset:32
	ds_read_b64_tr_b16 v[86:87], v250 offset:2304
	ds_read_b64_tr_b16 v[88:89], v250 offset:2880
	ds_read_b128 v[90:93], v249 offset:64
	ds_read_b64_tr_b16 v[94:95], v250 offset:4608
	ds_read_b64_tr_b16 v[96:97], v250 offset:5184
	s_waitcnt lgkmcnt(6)
	v_mfma_f32_32x32x16_bf16 v[66:81], v[4:7], v[8:11], 0
	ds_read_b128 v[4:7], v249 offset:96
	ds_read_b64_tr_b16 v[8:9], v250 offset:6912
	ds_read_b64_tr_b16 v[10:11], v250 offset:7488
	s_waitcnt lgkmcnt(6)
	v_mfma_f32_32x32x16_bf16 v[66:81], v[82:85], v[86:89], v[66:81]
	s_waitcnt lgkmcnt(3)
	v_mfma_f32_32x32x16_bf16 v[66:81], v[90:93], v[94:97], v[66:81]
	s_waitcnt lgkmcnt(0)
	v_mfma_f32_32x32x16_bf16 v[66:81], v[4:7], v[8:11], v[66:81]
	s_branch .LBB0_610
.Lmy_t6:
	ds_read_b128 v[4:7], v249
	ds_read_b64_tr_b16 v[8:9], v250
	ds_read_b64_tr_b16 v[10:11], v250 offset:576
	ds_read_b128 v[82:85], v249 offset:32
	ds_read_b64_tr_b16 v[86:87], v250 offset:2304
	ds_read_b64_tr_b16 v[88:89], v250 offset:2880
	ds_read_b128 v[90:93], v249 offset:64
	ds_read_b64_tr_b16 v[94:95], v250 offset:4608
	ds_read_b64_tr_b16 v[96:97], v250 offset:5184
	s_waitcnt lgkmcnt(6)
	v_mfma_f32_32x32x16_bf16 v[66:81], v[4:7], v[8:11], 0
	ds_read_b128 v[4:7], v249 offset:96
	ds_read_b64_tr_b16 v[8:9], v250 offset:6912
	ds_read_b64_tr_b16 v[10:11], v250 offset:7488
	s_waitcnt lgkmcnt(6)
	v_mfma_f32_32x32x16_bf16 v[66:81], v[82:85], v[86:89], v[66:81]
	ds_read_b128 v[82:85], v249 offset:128
	ds_read_b64_tr_b16 v[86:87], v250 offset:9216
	ds_read_b64_tr_b16 v[88:89], v250 offset:9792
	s_waitcnt lgkmcnt(6)
	v_mfma_f32_32x32x16_bf16 v[66:81], v[90:93], v[94:97], v[66:81]
	ds_read_b128 v[90:93], v249 offset:160
	ds_read_b64_tr_b16 v[94:95], v250 offset:11520
	ds_read_b64_tr_b16 v[96:97], v250 offset:12096
	s_waitcnt lgkmcnt(6)
	v_mfma_f32_32x32x16_bf16 v[66:81], v[4:7], v[8:11], v[66:81]
	s_waitcnt lgkmcnt(3)
	v_mfma_f32_32x32x16_bf16 v[66:81], v[82:85], v[86:89], v[66:81]
	s_waitcnt lgkmcnt(0)
	v_mfma_f32_32x32x16_bf16 v[66:81], v[90:93], v[94:97], v[66:81]
	s_branch .LBB0_610
.Lmy_t8:
	ds_read_b128 v[4:7], v249
	ds_read_b64_tr_b16 v[8:9], v250
	ds_read_b64_tr_b16 v[10:11], v250 offset:576
	ds_read_b128 v[82:85], v249 offset:32
	ds_read_b64_tr_b16 v[86:87], v250 offset:2304
	ds_read_b64_tr_b16 v[88:89], v250 offset:2880
	ds_read_b128 v[90:93], v249 offset:64
	ds_read_b64_tr_b16 v[94:95], v250 offset:4608
	ds_read_b64_tr_b16 v[96:97], v250 offset:5184
	s_waitcnt lgkmcnt(6)
	v_mfma_f32_32x32x16_bf16 v[66:81], v[4:7], v[8:11], 0
	ds_read_b128 v[4:7], v249 offset:96
	ds_read_b64_tr_b16 v[8:9], v250 offset:6912
	ds_read_b64_tr_b16 v[10:11], v250 offset:7488
	s_waitcnt lgkmcnt(6)
	v_mfma_f32_32x32x16_bf16 v[66:81], v[82:85], v[86:89], v[66:81]
	ds_read_b128 v[82:85], v249 offset:128
	ds_read_b64_tr_b16 v[86:87], v250 offset:9216
	ds_read_b64_tr_b16 v[88:89], v250 offset:9792
	s_waitcnt lgkmcnt(6)
	v_mfma_f32_32x32x16_bf16 v[66:81], v[90:93], v[94:97], v[66:81]
	ds_read_b128 v[90:93], v249 offset:160
	ds_read_b64_tr_b16 v[94:95], v250 offset:11520
	ds_read_b64_tr_b16 v[96:97], v250 offset:12096
	s_waitcnt lgkmcnt(6)
	v_mfma_f32_32x32x16_bf16 v[66:81], v[4:7], v[8:11], v[66:81]
	ds_read_b128 v[4:7], v249 offset:192
	ds_read_b64_tr_b16 v[8:9], v250 offset:13824
	ds_read_b64_tr_b16 v[10:11], v250 offset:14400
	s_waitcnt lgkmcnt(6)
	v_mfma_f32_32x32x16_bf16 v[66:81], v[82:85], v[86:89], v[66:81]
	ds_read_b128 v[82:85], v249 offset:224
	ds_read_b64_tr_b16 v[86:87], v250 offset:16128
	ds_read_b64_tr_b16 v[88:89], v250 offset:16704
	s_waitcnt lgkmcnt(6)
	v_mfma_f32_32x32x16_bf16 v[66:81], v[90:93], v[94:97], v[66:81]
	s_waitcnt lgkmcnt(3)
	v_mfma_f32_32x32x16_bf16 v[66:81], v[4:7], v[8:11], v[66:81]
	s_waitcnt lgkmcnt(0)
	v_mfma_f32_32x32x16_bf16 v[66:81], v[82:85], v[86:89], v[66:81]

.LBB0_612:
	v_lshl_add_u64 v[4:5], s[82:83], 0, v[184:185]
	v_mul_f32_e32 v8, v50, v228
	s_nop 5
	v_fmac_f32_e32 v8, v66, v198
	v_mul_f32_e32 v11, v51, v229
	v_fmac_f32_e32 v11, v67, v199
	v_mul_f32_e32 v13, v52, v230
	v_fmac_f32_e32 v13, v68, v200
	s_nop 0
	v_cvt_pk_bf16_f32 v10, v8, v11
	ds_write_b16 v154, v10
	ds_write_b16_d16_hi v154, v10 offset:64
	v_mul_f32_e32 v15, v53, v231
	v_fmac_f32_e32 v15, v69, v201
	s_nop 0
	v_cvt_pk_bf16_f32 v14, v13, v15
	ds_write_b16 v154, v14 offset:128
	ds_write_b16_d16_hi v154, v14 offset:192
	v_mul_f32_e32 v17, v54, v232
	v_fmac_f32_e32 v17, v70, v206
	v_mul_f32_e32 v51, v55, v233
	v_fmac_f32_e32 v51, v71, v207
	v_cvt_pk_bf16_f32 v50, v17, v51
	ds_write_b16 v154, v50 offset:512
	ds_write_b16_d16_hi v154, v50 offset:576
	v_mul_f32_e32 v53, v56, v234
	v_fmac_f32_e32 v53, v72, v208
	v_mul_f32_e32 v55, v57, v235
	v_fmac_f32_e32 v55, v73, v209
	s_nop 0
	v_cvt_pk_bf16_f32 v54, v53, v55
	ds_write_b16 v154, v54 offset:640
	ds_write_b16_d16_hi v154, v54 offset:704
	v_mul_f32_e32 v57, v58, v236
	v_fmac_f32_e32 v57, v74, v210
	s_nop 0
	v_mul_f32_e32 v59, v59, v237
	v_fmac_f32_e32 v59, v75, v211
	v_cvt_pk_bf16_f32 v58, v57, v59
	ds_write_b16 v154, v58 offset:1024
	ds_write_b16_d16_hi v154, v58 offset:1088
	v_mul_f32_e32 v60, v60, v238
	v_fmac_f32_e32 v60, v76, v212
	s_nop 0
	v_mul_f32_e32 v61, v61, v239
	v_fmac_f32_e32 v61, v77, v213
	v_cvt_pk_bf16_f32 v67, v60, v61
	ds_write_b16 v154, v67 offset:1152
	ds_write_b16_d16_hi v154, v67 offset:1216
	v_mul_f32_e32 v62, v62, v240
	v_fmac_f32_e32 v62, v78, v214
	s_nop 0
	v_mul_f32_e32 v63, v63, v241
	v_fmac_f32_e32 v63, v79, v215
	v_cvt_pk_bf16_f32 v69, v62, v63
	ds_write_b16 v154, v69 offset:1536
	ds_write_b16_d16_hi v154, v69 offset:1600
	v_mul_f32_e32 v7, v64, v242
	v_mul_f32_e32 v65, v65, v243
	v_fmac_f32_e32 v7, v80, v216
	v_fmac_f32_e32 v65, v81, v217
	v_cvt_pk_bf16_f32 v3, v7, v65
	ds_write_b16 v154, v3 offset:1664
	ds_write_b16_d16_hi v154, v3 offset:1728
	v_add_co_u32_e32 v194, vcc, v4, v156
	s_nop 1
	v_addc_co_u32_e32 v195, vcc, 0, v5, vcc
	v_add_co_u32_e32 v196, vcc, 0x10000, v194
	s_nop 1
	v_addc_co_u32_e32 v197, vcc, 0, v195, vcc
	s_waitcnt lgkmcnt(0)
	ds_read_b128 v[160:163], v155
	ds_read_b128 v[164:167], v155 offset:1024
	s_mov_b32 vcc_lo, 0xaaaaaaaa
	s_mov_b32 vcc_hi, 0xaaaaaaaa
	v_cndmask_b32_e32 v3, v8, v11, vcc
	v_cndmask_b32_e32 v4, v13, v15, vcc
	v_cndmask_b32_e32 v5, v17, v51, vcc
	v_cndmask_b32_e32 v6, v53, v55, vcc
	v_cndmask_b32_e32 v9, v57, v59, vcc
	v_cndmask_b32_e32 v10, v60, v61, vcc
	v_cndmask_b32_e32 v12, v62, v63, vcc
	v_cndmask_b32_e32 v14, v7, v65, vcc
	v_cndmask_b32_e32 v11, v11, v8, vcc
	v_cndmask_b32_e32 v15, v15, v13, vcc
	v_cndmask_b32_e32 v51, v51, v17, vcc
	v_cndmask_b32_e32 v55, v55, v53, vcc
	v_cndmask_b32_e32 v59, v59, v57, vcc
	v_cndmask_b32_e32 v61, v61, v60, vcc
	v_cndmask_b32_e32 v63, v63, v62, vcc
	v_cndmask_b32_e32 v65, v65, v7, vcc
	v_mul_f32_e32 v8, v3, v3
	v_mul_f32_e32 v13, v4, v4
	v_mul_f32_e32 v17, v5, v5
	v_mul_f32_e32 v53, v6, v6
	v_mul_f32_e32 v57, v9, v9
	v_mul_f32_e32 v60, v10, v10
	v_mul_f32_e32 v62, v12, v12
	v_mul_f32_e32 v7, v14, v14
	v_mul_f32_e32 v11, v11, v11
	v_mul_f32_e32 v15, v15, v15
	v_mul_f32_e32 v51, v51, v51
	v_mul_f32_e32 v55, v55, v55
	v_mul_f32_e32 v59, v59, v59
	v_mul_f32_e32 v61, v61, v61
	v_mul_f32_e32 v63, v63, v63
	v_mul_f32_e32 v65, v65, v65
	v_add_f32_dpp v8, v11, v8 quad_perm:[1,0,3,2] row_mask:0xf bank_mask:0xf
	v_add_f32_dpp v13, v15, v13 quad_perm:[1,0,3,2] row_mask:0xf bank_mask:0xf
	v_add_f32_dpp v17, v51, v17 quad_perm:[1,0,3,2] row_mask:0xf bank_mask:0xf
	v_add_f32_dpp v53, v55, v53 quad_perm:[1,0,3,2] row_mask:0xf bank_mask:0xf
	v_add_f32_dpp v57, v59, v57 quad_perm:[1,0,3,2] row_mask:0xf bank_mask:0xf
	v_add_f32_dpp v60, v61, v60 quad_perm:[1,0,3,2] row_mask:0xf bank_mask:0xf
	v_add_f32_dpp v62, v63, v62 quad_perm:[1,0,3,2] row_mask:0xf bank_mask:0xf
	v_add_f32_dpp v7, v65, v7 quad_perm:[1,0,3,2] row_mask:0xf bank_mask:0xf
	s_mov_b32 vcc_lo, 0xcccccccc
	s_mov_b32 vcc_hi, 0xcccccccc
	v_add_f32_dpp v8, v8, v8 quad_perm:[2,3,0,1] row_mask:0xf bank_mask:0xf
	v_add_f32_dpp v13, v13, v13 quad_perm:[2,3,0,1] row_mask:0xf bank_mask:0xf
	v_add_f32_dpp v17, v17, v17 quad_perm:[2,3,0,1] row_mask:0xf bank_mask:0xf
	v_add_f32_dpp v53, v53, v53 quad_perm:[2,3,0,1] row_mask:0xf bank_mask:0xf
	v_add_f32_dpp v57, v57, v57 quad_perm:[2,3,0,1] row_mask:0xf bank_mask:0xf
	v_add_f32_dpp v60, v60, v60 quad_perm:[2,3,0,1] row_mask:0xf bank_mask:0xf
	v_add_f32_dpp v62, v62, v62 quad_perm:[2,3,0,1] row_mask:0xf bank_mask:0xf
	v_add_f32_dpp v7, v7, v7 quad_perm:[2,3,0,1] row_mask:0xf bank_mask:0xf
	v_cndmask_b32_e32 v8, v8, v13, vcc
	v_cndmask_b32_e32 v17, v17, v53, vcc
	v_cndmask_b32_e32 v57, v57, v60, vcc
	v_cndmask_b32_e32 v62, v62, v7, vcc
	s_nop 1
	v_add_f32_dpp v16, v8, v8 row_shl:4 row_mask:0xf bank_mask:0x5
	v_add_f32_dpp v16, v17, v17 row_shr:4 row_mask:0xf bank_mask:0xa
	v_add_f32_dpp v50, v57, v57 row_shl:4 row_mask:0xf bank_mask:0x5
	v_add_f32_dpp v50, v62, v62 row_shr:4 row_mask:0xf bank_mask:0xa
	s_nop 1
	v_add_f32_dpp v12, v16, v16 row_shl:8 row_mask:0xf bank_mask:0x3
	v_add_f32_dpp v12, v50, v50 row_shr:8 row_mask:0xf bank_mask:0xc
	s_waitcnt lgkmcnt(0)
	global_store_dwordx4 v[194:195], v[160:163], off
	global_store_dwordx4 v[196:197], v[164:167], off
	v_mov_b32_e32 v14, v12
	v_and_b32_e32 v50, 15, v0
	v_lshrrev_b32_e32 v51, 2, v50
	v_and_b32_e32 v50, 3, v50
	v_lshlrev_b32_e32 v51, 11, v51
	v_lshl_or_b32 v50, v50, 8, v51
	v_add_u32_e32 v50, 0x200000, v50
	v_lshl_add_u64 v[4:5], s[82:83], 0, v[182:183]
	v_permlane16_swap_b32_e32 v12, v14
	v_add_co_u32_e32 v4, vcc, v4, v50
	v_add_f32_e32 v12, v12, v14
	s_nop 0
	v_addc_co_u32_e32 v5, vcc, 0, v5, vcc
	s_mov_b64 s[70:71], exec
	s_mov_b32 exec_lo, 0xffff
	s_mov_b32 exec_hi, 0xffff
	global_store_dword v[4:5], v12, off
	s_branch .LBB0_592
.LBB0_616:
	v_readlane_b32 s74, v255, 12
	v_readlane_b32 s75, v255, 13
	s_load_dwordx2 s[92:93], s[74:75], 0x88
	v_readlane_b32 s91, v255, 14
	v_readlane_b32 s90, v255, 11
